# v89 + p34_plain_safe2 (OR-mask placement words): P3 merged / P4 xmb+SSQ write-back, read from the producer XCD's L2; placement verified inside barrier 0's XCNT scan; write-back fallback
# speedup vs baseline: 1.0057x; 1.0057x over previous
.LBB0_2:
	s_or_b64 exec, exec, s[4:5]
	s_load_dwordx16 s[40:55], s[0:1], 0x0
	s_waitcnt lgkmcnt(0)
	s_barrier
	s_add_u32 s88, s80, 0x2380000
	s_getreg_b32 s4, hwreg(HW_REG_XCC_ID, 0, 4)
	s_addc_u32 s89, s81, 0
	s_and_b32 s87, s4, 15
	s_and_saveexec_b64 s[4:5], s[94:95]
	s_cbranch_execz .LBB0_5
	s_mov_b64 s[6:7], exec
	v_mbcnt_lo_u32_b32 v1, s6, 0
	v_mbcnt_hi_u32_b32 v1, s7, v1
	v_cmp_eq_u32_e32 vcc, 0, v1
	s_and_b64 s[8:9], exec, vcc
	s_mov_b64 exec, s[8:9]
	s_cbranch_execz .LBB0_5
	s_lshl_b32 s8, s87, 8
	s_bcnt1_i32_b64 s6, s[6:7]
	v_mov_b32_e32 v1, s8
	v_mov_b32_e32 v2, s6
	global_atomic_add v1, v2, s[88:89] offset:1024
	s_and_b32 s9, s2, 7
	s_lshl_b32 s9, s9, 6
	s_lshl_b32 s8, 1, s87
	v_mov_b32_e32 v3, s9
	v_mov_b32_e32 v4, s8
	global_atomic_or v3, v4, s[88:89]

.LBB0_35:
	s_waitcnt lgkmcnt(0)
	v_writelane_b32 v255, s56, 9
	s_cmp_gt_i32 s83, 1
	s_cselect_b64 s[0:1], -1, 0
	v_writelane_b32 v255, s57, 10
	v_writelane_b32 v255, s58, 11
	v_writelane_b32 v255, s59, 12
	v_writelane_b32 v255, s60, 13
	v_writelane_b32 v255, s61, 14
	v_writelane_b32 v255, s62, 15
	v_writelane_b32 v255, s63, 16
	v_writelane_b32 v255, s64, 17
	v_writelane_b32 v255, s65, 18
	v_writelane_b32 v255, s66, 19
	v_writelane_b32 v255, s67, 20
	v_writelane_b32 v255, s68, 21
	v_writelane_b32 v255, s69, 22
	s_and_b64 s[4:5], s[4:5], s[0:1]
	v_writelane_b32 v255, s70, 23
	s_andn2_b64 vcc, exec, s[4:5]
	v_writelane_b32 v255, s71, 24
	s_cbranch_vccnz .LBB0_89
	s_waitcnt vmcnt(0)
	s_barrier
	s_and_saveexec_b64 s[4:5], s[94:95]
	s_cbranch_execz .LBB0_88
	s_add_u32 s6, s80, 0x2380000
	s_addc_u32 s7, s81, 0
	s_mov_b64 exec, 0xffffff
	v_mbcnt_lo_u32_b32 v4, -1, 0
	v_lshlrev_b32_e32 v1, 6, v4
	v_subrev_u32_e32 v1, 0x400, v1
	v_lshlrev_b32_e32 v2, 8, v4
	v_add_u32_e32 v2, 0x400, v2
	v_cmp_gt_u32_e32 vcc, 16, v4
	s_nop 1
	v_cndmask_b32_e32 v2, v1, v2, vcc
	s_mov_b32 s10, 0

.Lxb0_ok:
	s_mov_b32 s32, 0
	v_readlane_b32 s8, v3, 16
	s_bcnt1_i32_b32 s8, s8
	s_cmp_lg_u32 s8, 1
	s_cselect_b32 s8, 1, 0
	s_or_b32 s32, s32, s8
	v_readlane_b32 s8, v3, 17
	s_bcnt1_i32_b32 s8, s8
	s_cmp_lg_u32 s8, 1
	s_cselect_b32 s8, 1, 0
	s_or_b32 s32, s32, s8
	v_readlane_b32 s8, v3, 18
	s_bcnt1_i32_b32 s8, s8
	s_cmp_lg_u32 s8, 1
	s_cselect_b32 s8, 1, 0
	s_or_b32 s32, s32, s8
	v_readlane_b32 s8, v3, 19
	s_bcnt1_i32_b32 s8, s8
	s_cmp_lg_u32 s8, 1
	s_cselect_b32 s8, 1, 0
	s_or_b32 s32, s32, s8
	v_readlane_b32 s8, v3, 20
	s_bcnt1_i32_b32 s8, s8
	s_cmp_lg_u32 s8, 1
	s_cselect_b32 s8, 1, 0
	s_or_b32 s32, s32, s8
	v_readlane_b32 s8, v3, 21
	s_bcnt1_i32_b32 s8, s8
	s_cmp_lg_u32 s8, 1
	s_cselect_b32 s8, 1, 0
	s_or_b32 s32, s32, s8
	v_readlane_b32 s8, v3, 22
	s_bcnt1_i32_b32 s8, s8
	s_cmp_lg_u32 s8, 1
	s_cselect_b32 s8, 1, 0
	s_or_b32 s32, s32, s8
	v_readlane_b32 s8, v3, 23
	s_bcnt1_i32_b32 s8, s8
	s_cmp_lg_u32 s8, 1
	s_cselect_b32 s8, 1, 0
	s_or_b32 s32, s32, s8
	s_cmp_lg_u32 s3, 0x100
	s_cselect_b32 s8, 1, 0
	s_or_b32 s32, s32, s8
	s_mov_b64 exec, 0xffff
	v_cmp_ne_u32_e32 vcc, 0, v3
	s_nop 3
	v_readlane_b32 s16, v3, s87
	s_bcnt1_i32_b64 s9, vcc
	s_max_u32 s16, s16, 1
	s_max_u32 s9, s9, 1
	s_mov_b64 exec, 1
	v_mov_b32_e32 v1, 0x23ff0
	v_mov_b32_e32 v2, s16
	v_mov_b32_e32 v3, s9
	ds_write_b32 v1, v2
	ds_write_b32 v1, v3 offset:4
	s_waitcnt lgkmcnt(0)
	v_mov_b32_e32 v1, 0x23ff0
	ds_read_b32 v2, v1
	ds_read_b32 v3, v1 offset:4
	s_add_u32 s6, s80, 0x2380000
	s_addc_u32 s7, s81, 0
	s_lshl_b32 s8, s87, 8
	s_add_i32 s9, s8, 0x1400
	s_add_i32 s8, s8, 0x2400
	v_mov_b32_e32 v4, s9
	v_mov_b32_e32 v5, 1
	global_atomic_add v6, v4, v5, s[6:7] sc0
	buffer_inv sc1
	s_waitcnt vmcnt(0) lgkmcnt(0)
	v_readfirstlane_b32 s10, v6
	v_readfirstlane_b32 s11, v2
	v_readfirstlane_b32 s16, v3
	s_add_i32 s10, s10, 1
	s_mul_i32 s11, s11, 1
	s_cmp_lg_u32 s10, s11
	s_cbranch_scc1 .Lxb_nl_0
	buffer_wbl2 sc1
	s_waitcnt vmcnt(0)
	v_mov_b32_e32 v4, 0x3400
	global_atomic_add v6, v4, v5, s[6:7] sc0
	s_waitcnt vmcnt(0)
	v_readfirstlane_b32 s10, v6
	s_add_i32 s10, s10, 1
	s_mul_i32 s16, s16, 1
	s_cmp_lg_u32 s10, s16
	s_cbranch_scc1 .Lxb_nl_0
	v_mov_b32_e32 v4, 0x2400
	global_atomic_add v4, v5, s[6:7]
	global_atomic_add v4, v5, s[6:7] offset:256
	global_atomic_add v4, v5, s[6:7] offset:512
	global_atomic_add v4, v5, s[6:7] offset:768
	global_atomic_add v4, v5, s[6:7] offset:1024
	global_atomic_add v4, v5, s[6:7] offset:1280
	global_atomic_add v4, v5, s[6:7] offset:1536
	global_atomic_add v4, v5, s[6:7] offset:1792
	global_atomic_add v4, v5, s[6:7] offset:2048
	global_atomic_add v4, v5, s[6:7] offset:2304
	global_atomic_add v4, v5, s[6:7] offset:2560
	global_atomic_add v4, v5, s[6:7] offset:2816
	global_atomic_add v4, v5, s[6:7] offset:3072
	global_atomic_add v4, v5, s[6:7] offset:3328
	global_atomic_add v4, v5, s[6:7] offset:3584
	global_atomic_add v4, v5, s[6:7] offset:3840
	s_branch .Lxb_done_0
